# P7 prompt items: LDS fragment reads for QK/PV MFMA chains issued through an 8-deep register ring (counted lgkmcnt) instead of read-wait-mfma pairs
# speedup vs baseline: 1.1642x; 1.0158x over previous
; #define MFMA(a, b, c) __builtin_amdgcn_mfma_f32_16x16x32_bf16((a), (b), (c), 0, 0, 0)
; DI void mem_attn_prompt_block(const Params& p, int item, char* smem) {
;   const int tid = threadIdx.x, lane = tid & 63, w = tid >> 6, r = lane & 15, kg = lane >> 4;
;   const int h = item & 3, qb = item >> 2;
;   const int row0 = qb * 64 + w * 16, b = (qb * 64) >> 13;
;   const int bh = b * 4 + h;
;   u16* sK = (u16*)smem;
;   bf16x8 qf[8];
; #pragma unroll
;   for (int ks = 0; ks < 8; ++ks) qf[ks] = *(const bf16x8*)&G(p.qb)[(size_t)(row0 + r) * 1024 + h * 256 + ks * 32 + kg * 8];
;   f32x4 st[16];
;   const u16* kbp = G(p.Kb) + (size_t)bh * 65536;
; #pragma unroll
;   for (int c = 0; c < 4; ++c) {
;     __syncthreads();
; #pragma unroll
;     for (int i2 = 0; i2 < 2; ++i2) {
; #pragma unroll
;       for (int i = i2 * 4; i < i2 * 4 + 4; ++i) {
;         const int idx = tid + 256 * i, row = idx >> 5, seg = idx & 31;
;         *(bf16x8*)&sK[row * 264 + seg * 8] = *(gb8p)((gu16p)kbp + (size_t)(c * 64 + row) * 256 + seg * 8);
;       }
;       __builtin_amdgcn_sched_barrier(0);
;     }
;     __syncthreads();
; #pragma unroll
;     for (int m4 = 0; m4 < 4; ++m4) {
;       f32x4 a = (f32x4){0.f, 0.f, 0.f, 0.f};
; #pragma unroll
;       for (int ks = 0; ks < 8; ++ks) {
;         bf16x8 kf = *(const bf16x8*)&sK[(m4 * 16 + r) * 264 + ks * 32 + kg * 8];
;         a = MFMA(kf, qf[ks], a);
;       }
;       st[c * 4 + m4] = a;
;       __builtin_amdgcn_sched_barrier(0);
;     }
;   }
.LBB0_887:
	s_cmp_gt_i32 s48, 31
	s_mov_b64 s[24:25], -1
	s_cbranch_scc0 .LBB0_891
	s_sub_i32 s0, s48, 32
	s_lshl_b32 s25, s0, 4
	ds_read_b64 v[0:1], v126
	ds_read_b64 v[4:5], v127
	s_and_b32 s24, s48, 3
	s_and_b32 s25, s25, 0x7fc0
	v_add_lshl_u32 v2, v120, s25, 10
	s_lshl_b32 s25, s24, 8
	v_or3_b32 v2, v2, s25, v172
	v_lshlrev_b32_e32 v2, 1, v2
	v_mov_b32_e32 v3, v95
	s_lshr_b32 s0, s0, 7
	s_waitcnt lgkmcnt(0)
	v_lshl_add_u64 v[0:1], v[0:1], 0, v[2:3]
	s_and_b32 s0, s0, 12
	flat_load_dwordx4 v[44:47], v[0:1]
	flat_load_dwordx4 v[40:43], v[0:1] offset:64
	flat_load_dwordx4 v[36:39], v[0:1] offset:128
	flat_load_dwordx4 v[32:35], v[0:1] offset:192
	flat_load_dwordx4 v[28:31], v[0:1] offset:256
	flat_load_dwordx4 v[24:27], v[0:1] offset:320
	flat_load_dwordx4 v[16:19], v[0:1] offset:384
	flat_load_dwordx4 v[20:23], v[0:1] offset:448
	s_or_b32 s0, s0, s24
	s_lshl_b32 s0, s0, 17
	v_lshl_add_u64 v[0:1], v[4:5], 0, s[0:1]
	v_mov_b32_e32 v115, v95
	v_lshl_add_u64 v[48:49], v[0:1], 0, v[114:115]
	v_lshl_add_u64 v[80:81], v[48:49], 0, v[96:97]
	v_lshl_add_u64 v[90:91], v[48:49], 0, v[100:101]
	s_waitcnt lgkmcnt(0)
	s_barrier
	v_lshl_add_u64 v[118:119], v[48:49], 0, v[98:99]
	global_load_dwordx4 v[0:3], v[80:81], off
	global_load_dwordx4 v[4:7], v[118:119], off
	v_lshl_add_u64 v[86:87], v[48:49], 0, v[102:103]
	global_load_dwordx4 v[8:11], v[90:91], off
	global_load_dwordx4 v[12:15], v[86:87], off
	s_and_b32 s24, s27, 0x7fc0
	v_add_u32_e32 v50, s24, v120
	s_and_b32 s25, s47, 3
	v_lshl_or_b32 v50, v50, 11, v125
	v_lshl_or_b32 v50, s25, 9, v50
	v_or_b32_e32 v94, 0x60, v50
	v_lshl_add_u64 v[204:205], v[48:49], 0, v[104:105]
	v_lshl_add_u64 v[84:85], v[48:49], 0, v[108:109]
	v_lshl_add_u64 v[88:89], v[48:49], 0, v[106:107]
	global_load_dwordx4 v[204:207], v[204:205], off
	s_nop 0
	global_load_dwordx4 v[208:211], v[88:89], off
	v_lshl_add_u64 v[82:83], v[48:49], 0, v[110:111]
	global_load_dwordx4 v[212:215], v[84:85], off
	global_load_dwordx4 v[216:219], v[82:83], off
	s_waitcnt vmcnt(4)
	ds_write_b128 v130, v[0:3]
	ds_write_b128 v131, v[4:7]
	ds_write_b128 v137, v[8:11]
	ds_write_b128 v142, v[12:15]
	s_waitcnt vmcnt(3)
	ds_write_b128 v130, v[204:207] offset:16896
	s_waitcnt vmcnt(2)
	ds_write_b128 v145, v[208:211]
	s_waitcnt vmcnt(1)
	ds_write_b128 v146, v[212:215]
	s_waitcnt vmcnt(0)
	ds_write_b128 v147, v[216:219]
	s_waitcnt lgkmcnt(0)
	s_barrier
	ds_read_b128 v[220:223], v121
	ds_read_b128 v[224:227], v121 offset:64
	ds_read_b128 v[228:231], v121 offset:128
	ds_read_b128 v[232:235], v121 offset:192
	ds_read_b128 v[236:239], v121 offset:256
	ds_read_b128 v[240:243], v121 offset:320
	ds_read_b128 v[244:247], v121 offset:384
	ds_read_b128 v[248:251], v121 offset:448
	s_waitcnt lgkmcnt(7)
	v_mfma_f32_16x16x32_bf16 v[0:3], v[220:223], v[44:47], 0
	ds_read_b128 v[220:223], v121 offset:8448
	s_waitcnt lgkmcnt(7)
	v_mfma_f32_16x16x32_bf16 v[0:3], v[224:227], v[40:43], v[0:3]
	ds_read_b128 v[224:227], v121 offset:8512
	s_waitcnt lgkmcnt(7)
	v_mfma_f32_16x16x32_bf16 v[0:3], v[228:231], v[36:39], v[0:3]
	ds_read_b128 v[228:231], v121 offset:8576
	s_waitcnt lgkmcnt(7)
	v_mfma_f32_16x16x32_bf16 v[0:3], v[232:235], v[32:35], v[0:3]
	ds_read_b128 v[232:235], v121 offset:8640
	s_waitcnt lgkmcnt(7)
	v_mfma_f32_16x16x32_bf16 v[0:3], v[236:239], v[28:31], v[0:3]
	ds_read_b128 v[236:239], v121 offset:8704
	s_waitcnt lgkmcnt(7)
	v_mfma_f32_16x16x32_bf16 v[0:3], v[240:243], v[24:27], v[0:3]
	ds_read_b128 v[240:243], v121 offset:8768
	s_waitcnt lgkmcnt(7)
	v_mfma_f32_16x16x32_bf16 v[0:3], v[244:247], v[16:19], v[0:3]
	ds_read_b128 v[244:247], v121 offset:8832
	s_waitcnt lgkmcnt(7)
	v_mfma_f32_16x16x32_bf16 v[0:3], v[248:251], v[20:23], v[0:3]
	ds_read_b128 v[248:251], v121 offset:8896
	s_waitcnt lgkmcnt(7)
	v_mfma_f32_16x16x32_bf16 v[4:7], v[220:223], v[44:47], 0
	ds_read_b128 v[220:223], v121 offset:16896
	s_waitcnt lgkmcnt(7)
	v_mfma_f32_16x16x32_bf16 v[4:7], v[224:227], v[40:43], v[4:7]
	ds_read_b128 v[224:227], v121 offset:16960
	s_waitcnt lgkmcnt(7)
	v_mfma_f32_16x16x32_bf16 v[4:7], v[228:231], v[36:39], v[4:7]
	ds_read_b128 v[228:231], v121 offset:17024
	s_waitcnt lgkmcnt(7)
	v_mfma_f32_16x16x32_bf16 v[4:7], v[232:235], v[32:35], v[4:7]
	ds_read_b128 v[232:235], v121 offset:17088
	s_waitcnt lgkmcnt(7)
	v_mfma_f32_16x16x32_bf16 v[4:7], v[236:239], v[28:31], v[4:7]
	ds_read_b128 v[236:239], v121 offset:17152
	s_waitcnt lgkmcnt(7)
	v_mfma_f32_16x16x32_bf16 v[4:7], v[240:243], v[24:27], v[4:7]
	ds_read_b128 v[240:243], v121 offset:17216
	s_waitcnt lgkmcnt(7)
	v_mfma_f32_16x16x32_bf16 v[4:7], v[244:247], v[16:19], v[4:7]
	ds_read_b128 v[244:247], v121 offset:17280
	s_waitcnt lgkmcnt(7)
	v_mfma_f32_16x16x32_bf16 v[4:7], v[248:251], v[20:23], v[4:7]
	ds_read_b128 v[248:251], v121 offset:17344
	s_waitcnt lgkmcnt(7)
	v_mfma_f32_16x16x32_bf16 v[8:11], v[220:223], v[44:47], 0
	ds_read_b128 v[220:223], v121 offset:25344
	s_waitcnt lgkmcnt(7)
	v_mfma_f32_16x16x32_bf16 v[8:11], v[224:227], v[40:43], v[8:11]
	ds_read_b128 v[224:227], v121 offset:25408
	s_waitcnt lgkmcnt(7)
	v_mfma_f32_16x16x32_bf16 v[8:11], v[228:231], v[36:39], v[8:11]
	ds_read_b128 v[228:231], v121 offset:25472
	s_waitcnt lgkmcnt(7)
	v_mfma_f32_16x16x32_bf16 v[8:11], v[232:235], v[32:35], v[8:11]
	ds_read_b128 v[232:235], v121 offset:25536
	s_waitcnt lgkmcnt(7)
	v_mfma_f32_16x16x32_bf16 v[8:11], v[236:239], v[28:31], v[8:11]
	ds_read_b128 v[236:239], v121 offset:25600
	s_waitcnt lgkmcnt(7)
	v_mfma_f32_16x16x32_bf16 v[8:11], v[240:243], v[24:27], v[8:11]
	ds_read_b128 v[240:243], v121 offset:25664
	s_waitcnt lgkmcnt(7)
	v_mfma_f32_16x16x32_bf16 v[8:11], v[244:247], v[16:19], v[8:11]
	ds_read_b128 v[244:247], v121 offset:25728
	s_waitcnt lgkmcnt(7)
	v_mfma_f32_16x16x32_bf16 v[8:11], v[248:251], v[20:23], v[8:11]
	ds_read_b128 v[248:251], v121 offset:25792
	s_waitcnt lgkmcnt(7)
	v_mfma_f32_16x16x32_bf16 v[12:15], v[220:223], v[44:47], 0
	s_waitcnt lgkmcnt(6)
	v_mfma_f32_16x16x32_bf16 v[12:15], v[224:227], v[40:43], v[12:15]
	s_waitcnt lgkmcnt(5)
	v_mfma_f32_16x16x32_bf16 v[12:15], v[228:231], v[36:39], v[12:15]
	s_waitcnt lgkmcnt(4)
	v_mfma_f32_16x16x32_bf16 v[12:15], v[232:235], v[32:35], v[12:15]
	s_waitcnt lgkmcnt(3)
	v_mfma_f32_16x16x32_bf16 v[12:15], v[236:239], v[28:31], v[12:15]
	s_waitcnt lgkmcnt(2)
	v_mfma_f32_16x16x32_bf16 v[12:15], v[240:243], v[24:27], v[12:15]
	s_waitcnt lgkmcnt(1)
	v_mfma_f32_16x16x32_bf16 v[12:15], v[244:247], v[16:19], v[12:15]
	s_waitcnt lgkmcnt(0)
	v_mfma_f32_16x16x32_bf16 v[12:15], v[248:251], v[20:23], v[12:15]
	v_add_co_u32_e32 v48, vcc, s28, v80
	s_nop 1
	v_addc_co_u32_e32 v49, vcc, 0, v81, vcc
	v_add_co_u32_e32 v52, vcc, s28, v118
	s_barrier
; #define MFMA(a, b, c) __builtin_amdgcn_mfma_f32_16x16x32_bf16((a), (b), (c), 0, 0, 0)
; DI void mem_attn_prompt_block(const Params& p, int item, char* smem) {
;     ...
; #pragma unroll
;   for (int c = 0; c < 4; ++c) {
;     __syncthreads();
; #pragma unroll
;     for (int i2 = 0; i2 < 2; ++i2) {
; #pragma unroll
;       for (int i = i2 * 4; i < i2 * 4 + 4; ++i) {
;         const int idx = tid + 256 * i, row = idx >> 5, seg = idx & 31;
;         *(bf16x8*)&sK[row * 264 + seg * 8] = *(gb8p)((gu16p)kbp + (size_t)(c * 64 + row) * 256 + seg * 8);
;       }
;       __builtin_amdgcn_sched_barrier(0);
;     }
;     __syncthreads();
; #pragma unroll
;     for (int m4 = 0; m4 < 4; ++m4) {
;       f32x4 a = (f32x4){0.f, 0.f, 0.f, 0.f};
; #pragma unroll
;       for (int ks = 0; ks < 8; ++ks) {
;         bf16x8 kf = *(const bf16x8*)&sK[(m4 * 16 + r) * 264 + ks * 32 + kg * 8];
;         a = MFMA(kf, qf[ks], a);
;       }
;       st[c * 4 + m4] = a;
;       __builtin_amdgcn_sched_barrier(0);
;     }
;   }
	s_nop 0
	v_addc_co_u32_e32 v53, vcc, 0, v119, vcc
	v_add_co_u32_e32 v56, vcc, s28, v90
	s_nop 1
	v_addc_co_u32_e32 v57, vcc, 0, v91, vcc
	v_add_co_u32_e32 v60, vcc, s28, v86
	global_load_dwordx4 v[48:51], v[48:49], off
	s_nop 0
	global_load_dwordx4 v[52:55], v[52:53], off
	v_addc_co_u32_e32 v61, vcc, 0, v87, vcc
	global_load_dwordx4 v[56:59], v[56:57], off
	s_nop 0
	global_load_dwordx4 v[60:63], v[60:61], off
	v_add_co_u32_e32 v204, vcc, s29, v80
	s_nop 1
	v_addc_co_u32_e32 v205, vcc, 0, v81, vcc
	v_add_co_u32_e32 v208, vcc, s28, v88
	s_nop 1
	v_addc_co_u32_e32 v209, vcc, 0, v89, vcc
	v_add_co_u32_e32 v212, vcc, s28, v84
	global_load_dwordx4 v[204:207], v[204:205], off
	s_nop 0
	global_load_dwordx4 v[208:211], v[208:209], off
	v_addc_co_u32_e32 v213, vcc, 0, v85, vcc
	v_add_co_u32_e32 v216, vcc, s28, v82
	s_nop 1
	v_addc_co_u32_e32 v217, vcc, 0, v83, vcc
	global_load_dwordx4 v[212:215], v[212:213], off
	s_nop 0
	global_load_dwordx4 v[216:219], v[216:217], off
	s_waitcnt vmcnt(7)
	ds_write_b128 v130, v[48:51]
	s_waitcnt vmcnt(6)
	ds_write_b128 v131, v[52:55]
	s_waitcnt vmcnt(5)
	ds_write_b128 v137, v[56:59]
	s_waitcnt vmcnt(4)
	ds_write_b128 v142, v[60:63]
	s_waitcnt vmcnt(3)
	ds_write_b128 v130, v[204:207] offset:16896
	s_waitcnt vmcnt(2)
	ds_write_b128 v145, v[208:211]
	s_waitcnt vmcnt(1)
	ds_write_b128 v146, v[212:215]
	s_waitcnt vmcnt(0)
	ds_write_b128 v147, v[216:219]
	s_waitcnt lgkmcnt(0)
	s_barrier
	ds_read_b128 v[220:223], v121
	ds_read_b128 v[224:227], v121 offset:64
	ds_read_b128 v[228:231], v121 offset:128
	ds_read_b128 v[232:235], v121 offset:192
	ds_read_b128 v[236:239], v121 offset:256
	ds_read_b128 v[240:243], v121 offset:320
	ds_read_b128 v[244:247], v121 offset:384
	ds_read_b128 v[248:251], v121 offset:448
	s_waitcnt lgkmcnt(7)
	v_mfma_f32_16x16x32_bf16 v[48:51], v[220:223], v[44:47], 0
	ds_read_b128 v[220:223], v121 offset:8448
	s_waitcnt lgkmcnt(7)
	v_mfma_f32_16x16x32_bf16 v[48:51], v[224:227], v[40:43], v[48:51]
	ds_read_b128 v[224:227], v121 offset:8512
	s_waitcnt lgkmcnt(7)
	v_mfma_f32_16x16x32_bf16 v[48:51], v[228:231], v[36:39], v[48:51]
	ds_read_b128 v[228:231], v121 offset:8576
	s_waitcnt lgkmcnt(7)
	v_mfma_f32_16x16x32_bf16 v[48:51], v[232:235], v[32:35], v[48:51]
	ds_read_b128 v[232:235], v121 offset:8640
	s_waitcnt lgkmcnt(7)
	v_mfma_f32_16x16x32_bf16 v[48:51], v[236:239], v[28:31], v[48:51]
	ds_read_b128 v[236:239], v121 offset:8704
	s_waitcnt lgkmcnt(7)
	v_mfma_f32_16x16x32_bf16 v[48:51], v[240:243], v[24:27], v[48:51]
	ds_read_b128 v[240:243], v121 offset:8768
	s_waitcnt lgkmcnt(7)
	v_mfma_f32_16x16x32_bf16 v[48:51], v[244:247], v[16:19], v[48:51]
	ds_read_b128 v[244:247], v121 offset:8832
	s_waitcnt lgkmcnt(7)
	v_mfma_f32_16x16x32_bf16 v[48:51], v[248:251], v[20:23], v[48:51]
	ds_read_b128 v[248:251], v121 offset:8896
	s_waitcnt lgkmcnt(7)
	v_mfma_f32_16x16x32_bf16 v[52:55], v[220:223], v[44:47], 0
	ds_read_b128 v[220:223], v121 offset:16896
	s_waitcnt lgkmcnt(7)
	v_mfma_f32_16x16x32_bf16 v[52:55], v[224:227], v[40:43], v[52:55]
	ds_read_b128 v[224:227], v121 offset:16960
	s_waitcnt lgkmcnt(7)
	v_mfma_f32_16x16x32_bf16 v[52:55], v[228:231], v[36:39], v[52:55]
	ds_read_b128 v[228:231], v121 offset:17024
	s_waitcnt lgkmcnt(7)
	v_mfma_f32_16x16x32_bf16 v[52:55], v[232:235], v[32:35], v[52:55]
	ds_read_b128 v[232:235], v121 offset:17088
	s_waitcnt lgkmcnt(7)
	v_mfma_f32_16x16x32_bf16 v[52:55], v[236:239], v[28:31], v[52:55]
	ds_read_b128 v[236:239], v121 offset:17152
	s_waitcnt lgkmcnt(7)
	v_mfma_f32_16x16x32_bf16 v[52:55], v[240:243], v[24:27], v[52:55]
	ds_read_b128 v[240:243], v121 offset:17216
	s_waitcnt lgkmcnt(7)
	v_mfma_f32_16x16x32_bf16 v[52:55], v[244:247], v[16:19], v[52:55]
	ds_read_b128 v[244:247], v121 offset:17280
	s_waitcnt lgkmcnt(7)
	v_mfma_f32_16x16x32_bf16 v[52:55], v[248:251], v[20:23], v[52:55]
	ds_read_b128 v[248:251], v121 offset:17344
	s_waitcnt lgkmcnt(7)
	v_mfma_f32_16x16x32_bf16 v[56:59], v[220:223], v[44:47], 0
	ds_read_b128 v[220:223], v121 offset:25344
	s_waitcnt lgkmcnt(7)
	v_mfma_f32_16x16x32_bf16 v[56:59], v[224:227], v[40:43], v[56:59]
	ds_read_b128 v[224:227], v121 offset:25408
	s_waitcnt lgkmcnt(7)
	v_mfma_f32_16x16x32_bf16 v[56:59], v[228:231], v[36:39], v[56:59]
	ds_read_b128 v[228:231], v121 offset:25472
	s_waitcnt lgkmcnt(7)
	v_mfma_f32_16x16x32_bf16 v[56:59], v[232:235], v[32:35], v[56:59]
	ds_read_b128 v[232:235], v121 offset:25536
	s_waitcnt lgkmcnt(7)
	v_mfma_f32_16x16x32_bf16 v[56:59], v[236:239], v[28:31], v[56:59]
	ds_read_b128 v[236:239], v121 offset:25600
	s_waitcnt lgkmcnt(7)
	v_mfma_f32_16x16x32_bf16 v[56:59], v[240:243], v[24:27], v[56:59]
	ds_read_b128 v[240:243], v121 offset:25664
	s_waitcnt lgkmcnt(7)
	v_mfma_f32_16x16x32_bf16 v[56:59], v[244:247], v[16:19], v[56:59]
	ds_read_b128 v[244:247], v121 offset:25728
	s_waitcnt lgkmcnt(7)
	v_mfma_f32_16x16x32_bf16 v[56:59], v[248:251], v[20:23], v[56:59]
	ds_read_b128 v[248:251], v121 offset:25792
	s_waitcnt lgkmcnt(7)
	v_mfma_f32_16x16x32_bf16 v[60:63], v[220:223], v[44:47], 0
	s_waitcnt lgkmcnt(6)
	v_mfma_f32_16x16x32_bf16 v[60:63], v[224:227], v[40:43], v[60:63]
	s_waitcnt lgkmcnt(5)
	v_mfma_f32_16x16x32_bf16 v[60:63], v[228:231], v[36:39], v[60:63]
	s_waitcnt lgkmcnt(4)
	v_mfma_f32_16x16x32_bf16 v[60:63], v[232:235], v[32:35], v[60:63]
	s_waitcnt lgkmcnt(3)
	v_mfma_f32_16x16x32_bf16 v[60:63], v[236:239], v[28:31], v[60:63]
	s_waitcnt lgkmcnt(2)
	v_mfma_f32_16x16x32_bf16 v[60:63], v[240:243], v[24:27], v[60:63]
	s_waitcnt lgkmcnt(1)
	v_mfma_f32_16x16x32_bf16 v[60:63], v[244:247], v[16:19], v[60:63]
	s_waitcnt lgkmcnt(0)
	v_mfma_f32_16x16x32_bf16 v[60:63], v[248:251], v[20:23], v[60:63]
	v_add_co_u32_e32 v64, vcc, s30, v80
	s_nop 1
	v_addc_co_u32_e32 v65, vcc, 0, v81, vcc
	v_add_co_u32_e32 v68, vcc, s30, v118
	s_barrier
; #define MFMA(a, b, c) __builtin_amdgcn_mfma_f32_16x16x32_bf16((a), (b), (c), 0, 0, 0)
; DI void mem_attn_prompt_block(const Params& p, int item, char* smem) {
;     ...
; #pragma unroll
;   for (int c = 0; c < 4; ++c) {
;     __syncthreads();
; #pragma unroll
;     for (int i2 = 0; i2 < 2; ++i2) {
; #pragma unroll
;       for (int i = i2 * 4; i < i2 * 4 + 4; ++i) {
;         const int idx = tid + 256 * i, row = idx >> 5, seg = idx & 31;
;         *(bf16x8*)&sK[row * 264 + seg * 8] = *(gb8p)((gu16p)kbp + (size_t)(c * 64 + row) * 256 + seg * 8);
;       }
;       __builtin_amdgcn_sched_barrier(0);
;     }
;     __syncthreads();
; #pragma unroll
;     for (int m4 = 0; m4 < 4; ++m4) {
;       f32x4 a = (f32x4){0.f, 0.f, 0.f, 0.f};
; #pragma unroll
;       for (int ks = 0; ks < 8; ++ks) {
;         bf16x8 kf = *(const bf16x8*)&sK[(m4 * 16 + r) * 264 + ks * 32 + kg * 8];
;         a = MFMA(kf, qf[ks], a);
;       }
;       st[c * 4 + m4] = a;
;       __builtin_amdgcn_sched_barrier(0);
;     }
;   }
	s_nop 0
	v_addc_co_u32_e32 v69, vcc, 0, v119, vcc
	v_add_co_u32_e32 v72, vcc, s30, v90
	s_nop 1
	v_addc_co_u32_e32 v73, vcc, 0, v91, vcc
	v_add_co_u32_e32 v76, vcc, s30, v86
	global_load_dwordx4 v[64:67], v[64:65], off
	s_nop 0
	global_load_dwordx4 v[68:71], v[68:69], off
	v_addc_co_u32_e32 v77, vcc, 0, v87, vcc
	global_load_dwordx4 v[72:75], v[72:73], off
	s_nop 0
	global_load_dwordx4 v[76:79], v[76:77], off
	v_add_co_u32_e32 v204, vcc, s31, v80
	s_nop 1
	v_addc_co_u32_e32 v205, vcc, 0, v81, vcc
	v_add_co_u32_e32 v208, vcc, s30, v88
	s_nop 1
	v_addc_co_u32_e32 v209, vcc, 0, v89, vcc
	v_add_co_u32_e32 v212, vcc, s30, v84
	global_load_dwordx4 v[204:207], v[204:205], off
	s_nop 0
	global_load_dwordx4 v[208:211], v[208:209], off
	v_addc_co_u32_e32 v213, vcc, 0, v85, vcc
	v_add_co_u32_e32 v216, vcc, s30, v82
	s_nop 1
	v_addc_co_u32_e32 v217, vcc, 0, v83, vcc
	global_load_dwordx4 v[212:215], v[212:213], off
	s_nop 0
	global_load_dwordx4 v[216:219], v[216:217], off
	s_waitcnt vmcnt(7)
	ds_write_b128 v130, v[64:67]
	s_waitcnt vmcnt(6)
	ds_write_b128 v131, v[68:71]
	s_waitcnt vmcnt(5)
	ds_write_b128 v137, v[72:75]
	s_waitcnt vmcnt(4)
	ds_write_b128 v142, v[76:79]
	s_waitcnt vmcnt(3)
	ds_write_b128 v130, v[204:207] offset:16896
	s_waitcnt vmcnt(2)
	ds_write_b128 v145, v[208:211]
	s_waitcnt vmcnt(1)
	ds_write_b128 v146, v[212:215]
	s_waitcnt vmcnt(0)
	ds_write_b128 v147, v[216:219]
	s_waitcnt lgkmcnt(0)
	s_barrier
	ds_read_b128 v[220:223], v121
	ds_read_b128 v[224:227], v121 offset:64
	ds_read_b128 v[228:231], v121 offset:128
	ds_read_b128 v[232:235], v121 offset:192
	ds_read_b128 v[236:239], v121 offset:256
	ds_read_b128 v[240:243], v121 offset:320
	ds_read_b128 v[244:247], v121 offset:384
	ds_read_b128 v[248:251], v121 offset:448
	s_waitcnt lgkmcnt(7)
	v_mfma_f32_16x16x32_bf16 v[64:67], v[220:223], v[44:47], 0
	ds_read_b128 v[220:223], v121 offset:8448
	s_waitcnt lgkmcnt(7)
	v_mfma_f32_16x16x32_bf16 v[64:67], v[224:227], v[40:43], v[64:67]
	ds_read_b128 v[224:227], v121 offset:8512
	s_waitcnt lgkmcnt(7)
	v_mfma_f32_16x16x32_bf16 v[64:67], v[228:231], v[36:39], v[64:67]
	ds_read_b128 v[228:231], v121 offset:8576
	s_waitcnt lgkmcnt(7)
	v_mfma_f32_16x16x32_bf16 v[64:67], v[232:235], v[32:35], v[64:67]
	ds_read_b128 v[232:235], v121 offset:8640
	s_waitcnt lgkmcnt(7)
	v_mfma_f32_16x16x32_bf16 v[64:67], v[236:239], v[28:31], v[64:67]
	ds_read_b128 v[236:239], v121 offset:8704
	s_waitcnt lgkmcnt(7)
	v_mfma_f32_16x16x32_bf16 v[64:67], v[240:243], v[24:27], v[64:67]
	ds_read_b128 v[240:243], v121 offset:8768
	s_waitcnt lgkmcnt(7)
	v_mfma_f32_16x16x32_bf16 v[64:67], v[244:247], v[16:19], v[64:67]
	ds_read_b128 v[244:247], v121 offset:8832
	s_waitcnt lgkmcnt(7)
	v_mfma_f32_16x16x32_bf16 v[64:67], v[248:251], v[20:23], v[64:67]
	ds_read_b128 v[248:251], v121 offset:8896
	s_waitcnt lgkmcnt(7)
	v_mfma_f32_16x16x32_bf16 v[68:71], v[220:223], v[44:47], 0
	ds_read_b128 v[220:223], v121 offset:16896
	s_waitcnt lgkmcnt(7)
	v_mfma_f32_16x16x32_bf16 v[68:71], v[224:227], v[40:43], v[68:71]
	ds_read_b128 v[224:227], v121 offset:16960
	s_waitcnt lgkmcnt(7)
	v_mfma_f32_16x16x32_bf16 v[68:71], v[228:231], v[36:39], v[68:71]
	ds_read_b128 v[228:231], v121 offset:17024
	s_waitcnt lgkmcnt(7)
	v_mfma_f32_16x16x32_bf16 v[68:71], v[232:235], v[32:35], v[68:71]
	ds_read_b128 v[232:235], v121 offset:17088
	s_waitcnt lgkmcnt(7)
	v_mfma_f32_16x16x32_bf16 v[68:71], v[236:239], v[28:31], v[68:71]
	ds_read_b128 v[236:239], v121 offset:17152
	s_waitcnt lgkmcnt(7)
	v_mfma_f32_16x16x32_bf16 v[68:71], v[240:243], v[24:27], v[68:71]
	ds_read_b128 v[240:243], v121 offset:17216
	s_waitcnt lgkmcnt(7)
	v_mfma_f32_16x16x32_bf16 v[68:71], v[244:247], v[16:19], v[68:71]
	ds_read_b128 v[244:247], v121 offset:17280
	s_waitcnt lgkmcnt(7)
	v_mfma_f32_16x16x32_bf16 v[68:71], v[248:251], v[20:23], v[68:71]
	ds_read_b128 v[248:251], v121 offset:17344
	s_waitcnt lgkmcnt(7)
	v_mfma_f32_16x16x32_bf16 v[72:75], v[220:223], v[44:47], 0
	ds_read_b128 v[220:223], v121 offset:25344
	s_waitcnt lgkmcnt(7)
	v_mfma_f32_16x16x32_bf16 v[72:75], v[224:227], v[40:43], v[72:75]
	ds_read_b128 v[224:227], v121 offset:25408
	s_waitcnt lgkmcnt(7)
	v_mfma_f32_16x16x32_bf16 v[72:75], v[228:231], v[36:39], v[72:75]
	ds_read_b128 v[228:231], v121 offset:25472
	s_waitcnt lgkmcnt(7)
	v_mfma_f32_16x16x32_bf16 v[72:75], v[232:235], v[32:35], v[72:75]
	ds_read_b128 v[232:235], v121 offset:25536
	s_waitcnt lgkmcnt(7)
	v_mfma_f32_16x16x32_bf16 v[72:75], v[236:239], v[28:31], v[72:75]
	ds_read_b128 v[236:239], v121 offset:25600
	s_waitcnt lgkmcnt(7)
	v_mfma_f32_16x16x32_bf16 v[72:75], v[240:243], v[24:27], v[72:75]
	ds_read_b128 v[240:243], v121 offset:25664
	s_waitcnt lgkmcnt(7)
	v_mfma_f32_16x16x32_bf16 v[72:75], v[244:247], v[16:19], v[72:75]
	ds_read_b128 v[244:247], v121 offset:25728
	s_waitcnt lgkmcnt(7)
	v_mfma_f32_16x16x32_bf16 v[72:75], v[248:251], v[20:23], v[72:75]
	ds_read_b128 v[248:251], v121 offset:25792
	s_waitcnt lgkmcnt(7)
	v_mfma_f32_16x16x32_bf16 v[76:79], v[220:223], v[44:47], 0
	s_waitcnt lgkmcnt(6)
	v_mfma_f32_16x16x32_bf16 v[76:79], v[224:227], v[40:43], v[76:79]
	s_waitcnt lgkmcnt(5)
	v_mfma_f32_16x16x32_bf16 v[76:79], v[228:231], v[36:39], v[76:79]
	s_waitcnt lgkmcnt(4)
	v_mfma_f32_16x16x32_bf16 v[76:79], v[232:235], v[32:35], v[76:79]
	s_waitcnt lgkmcnt(3)
	v_mfma_f32_16x16x32_bf16 v[76:79], v[236:239], v[28:31], v[76:79]
	s_waitcnt lgkmcnt(2)
	v_mfma_f32_16x16x32_bf16 v[76:79], v[240:243], v[24:27], v[76:79]
	s_waitcnt lgkmcnt(1)
	v_mfma_f32_16x16x32_bf16 v[76:79], v[244:247], v[16:19], v[76:79]
	s_waitcnt lgkmcnt(0)
	v_mfma_f32_16x16x32_bf16 v[76:79], v[248:251], v[20:23], v[76:79]
	v_add_co_u32_e32 v156, vcc, s34, v80
	s_nop 1
	v_addc_co_u32_e32 v157, vcc, 0, v81, vcc
	v_add_co_u32_e32 v118, vcc, s34, v118
	s_barrier
; #define MFMA(a, b, c) __builtin_amdgcn_mfma_f32_16x16x32_bf16((a), (b), (c), 0, 0, 0)
; DI void mem_attn_prompt_block(const Params& p, int item, char* smem) {
;     ...
; #pragma unroll
;   for (int c = 0; c < 4; ++c) {
;     __syncthreads();
; #pragma unroll
;     for (int i2 = 0; i2 < 2; ++i2) {
; #pragma unroll
;       for (int i = i2 * 4; i < i2 * 4 + 4; ++i) {
;         const int idx = tid + 256 * i, row = idx >> 5, seg = idx & 31;
;         *(bf16x8*)&sK[row * 264 + seg * 8] = *(gb8p)((gu16p)kbp + (size_t)(c * 64 + row) * 256 + seg * 8);
;       }
;       __builtin_amdgcn_sched_barrier(0);
;     }
;     __syncthreads();
; #pragma unroll
;     for (int m4 = 0; m4 < 4; ++m4) {
;       f32x4 a = (f32x4){0.f, 0.f, 0.f, 0.f};
; #pragma unroll
;       for (int ks = 0; ks < 8; ++ks) {
;         bf16x8 kf = *(const bf16x8*)&sK[(m4 * 16 + r) * 264 + ks * 32 + kg * 8];
;         a = MFMA(kf, qf[ks], a);
;       }
;       st[c * 4 + m4] = a;
;       __builtin_amdgcn_sched_barrier(0);
;     }
;   }
	s_nop 0
	v_addc_co_u32_e32 v119, vcc, 0, v119, vcc
	v_add_co_u32_e32 v90, vcc, s34, v90
	s_nop 1
	v_addc_co_u32_e32 v91, vcc, 0, v91, vcc
	v_add_co_u32_e32 v86, vcc, s34, v86
	global_load_dwordx4 v[156:159], v[156:157], off
	s_nop 0
	global_load_dwordx4 v[166:169], v[118:119], off
	v_addc_co_u32_e32 v87, vcc, 0, v87, vcc
	global_load_dwordx4 v[192:195], v[90:91], off
	global_load_dwordx4 v[198:201], v[86:87], off
	v_add_co_u32_e32 v212, vcc, s35, v80
	s_nop 1
	v_addc_co_u32_e32 v213, vcc, 0, v81, vcc
	v_add_co_u32_e32 v90, vcc, s34, v88
	s_nop 1
	v_addc_co_u32_e32 v91, vcc, 0, v89, vcc
	global_load_dwordx4 v[204:207], v[212:213], off
	global_load_dwordx4 v[208:211], v[90:91], off
	v_add_co_u32_e32 v212, vcc, s34, v84
	s_nop 1
	v_addc_co_u32_e32 v213, vcc, 0, v85, vcc
	v_add_co_u32_e32 v84, vcc, s34, v82
	s_nop 1
	v_addc_co_u32_e32 v85, vcc, 0, v83, vcc
	global_load_dwordx4 v[212:215], v[212:213], off
	s_nop 0
	global_load_dwordx4 v[216:219], v[84:85], off
	s_waitcnt vmcnt(7)
	ds_write_b128 v130, v[156:159]
	s_waitcnt vmcnt(6)
	ds_write_b128 v131, v[166:169]
	s_waitcnt vmcnt(5)
	ds_write_b128 v137, v[192:195]
	s_waitcnt vmcnt(4)
	ds_write_b128 v142, v[198:201]
	s_waitcnt vmcnt(3)
	ds_write_b128 v130, v[204:207] offset:16896
	s_waitcnt vmcnt(2)
	ds_write_b128 v145, v[208:211]
	s_waitcnt vmcnt(1)
	ds_write_b128 v146, v[212:215]
	s_waitcnt vmcnt(0)
	ds_write_b128 v147, v[216:219]
	s_waitcnt lgkmcnt(0)
	s_barrier
	ds_read_b128 v[220:223], v121
	ds_read_b128 v[224:227], v121 offset:64
	ds_read_b128 v[228:231], v121 offset:128
	ds_read_b128 v[232:235], v121 offset:192
	ds_read_b128 v[236:239], v121 offset:256
	ds_read_b128 v[240:243], v121 offset:320
	ds_read_b128 v[244:247], v121 offset:384
	ds_read_b128 v[248:251], v121 offset:448
	s_waitcnt lgkmcnt(7)
	v_mfma_f32_16x16x32_bf16 v[80:83], v[220:223], v[44:47], 0
	ds_read_b128 v[220:223], v121 offset:8448
	s_waitcnt lgkmcnt(7)
	v_mfma_f32_16x16x32_bf16 v[80:83], v[224:227], v[40:43], v[80:83]
	ds_read_b128 v[224:227], v121 offset:8512
	s_waitcnt lgkmcnt(7)
	v_mfma_f32_16x16x32_bf16 v[80:83], v[228:231], v[36:39], v[80:83]
	ds_read_b128 v[228:231], v121 offset:8576
	s_waitcnt lgkmcnt(7)
	v_mfma_f32_16x16x32_bf16 v[80:83], v[232:235], v[32:35], v[80:83]
	ds_read_b128 v[232:235], v121 offset:8640
	s_waitcnt lgkmcnt(7)
	v_mfma_f32_16x16x32_bf16 v[80:83], v[236:239], v[28:31], v[80:83]
	ds_read_b128 v[236:239], v121 offset:8704
	s_waitcnt lgkmcnt(7)
	v_mfma_f32_16x16x32_bf16 v[80:83], v[240:243], v[24:27], v[80:83]
	ds_read_b128 v[240:243], v121 offset:8768
	s_waitcnt lgkmcnt(7)
	v_mfma_f32_16x16x32_bf16 v[80:83], v[244:247], v[16:19], v[80:83]
	ds_read_b128 v[244:247], v121 offset:8832
	s_waitcnt lgkmcnt(7)
	v_mfma_f32_16x16x32_bf16 v[80:83], v[248:251], v[20:23], v[80:83]
	ds_read_b128 v[248:251], v121 offset:8896
	s_waitcnt lgkmcnt(7)
	v_mfma_f32_16x16x32_bf16 v[84:87], v[220:223], v[44:47], 0
	ds_read_b128 v[220:223], v121 offset:16896
	s_waitcnt lgkmcnt(7)
	v_mfma_f32_16x16x32_bf16 v[84:87], v[224:227], v[40:43], v[84:87]
	ds_read_b128 v[224:227], v121 offset:16960
	s_waitcnt lgkmcnt(7)
	v_mfma_f32_16x16x32_bf16 v[84:87], v[228:231], v[36:39], v[84:87]
	ds_read_b128 v[228:231], v121 offset:17024
	s_waitcnt lgkmcnt(7)
	v_mfma_f32_16x16x32_bf16 v[84:87], v[232:235], v[32:35], v[84:87]
	ds_read_b128 v[232:235], v121 offset:17088
	s_waitcnt lgkmcnt(7)
	v_mfma_f32_16x16x32_bf16 v[84:87], v[236:239], v[28:31], v[84:87]
	ds_read_b128 v[236:239], v121 offset:17152
	s_waitcnt lgkmcnt(7)
	v_mfma_f32_16x16x32_bf16 v[84:87], v[240:243], v[24:27], v[84:87]
	ds_read_b128 v[240:243], v121 offset:17216
	s_waitcnt lgkmcnt(7)
	v_mfma_f32_16x16x32_bf16 v[84:87], v[244:247], v[16:19], v[84:87]
	ds_read_b128 v[244:247], v121 offset:17280
	s_waitcnt lgkmcnt(7)
	v_mfma_f32_16x16x32_bf16 v[84:87], v[248:251], v[20:23], v[84:87]
	ds_read_b128 v[248:251], v121 offset:17344
	s_waitcnt lgkmcnt(7)
	v_mfma_f32_16x16x32_bf16 v[88:91], v[220:223], v[44:47], 0
	ds_read_b128 v[220:223], v121 offset:25344
	s_waitcnt lgkmcnt(7)
	v_mfma_f32_16x16x32_bf16 v[88:91], v[224:227], v[40:43], v[88:91]
	ds_read_b128 v[224:227], v121 offset:25408
	s_waitcnt lgkmcnt(7)
	v_mfma_f32_16x16x32_bf16 v[88:91], v[228:231], v[36:39], v[88:91]
	ds_read_b128 v[228:231], v121 offset:25472
	s_waitcnt lgkmcnt(7)
	v_mfma_f32_16x16x32_bf16 v[88:91], v[232:235], v[32:35], v[88:91]
	ds_read_b128 v[232:235], v121 offset:25536
	s_waitcnt lgkmcnt(7)
	v_mfma_f32_16x16x32_bf16 v[88:91], v[236:239], v[28:31], v[88:91]
	ds_read_b128 v[236:239], v121 offset:25600
	s_waitcnt lgkmcnt(7)
	v_mfma_f32_16x16x32_bf16 v[88:91], v[240:243], v[24:27], v[88:91]
	ds_read_b128 v[240:243], v121 offset:25664
	s_waitcnt lgkmcnt(7)
	v_mfma_f32_16x16x32_bf16 v[88:91], v[244:247], v[16:19], v[88:91]
	ds_read_b128 v[244:247], v121 offset:25728
	s_waitcnt lgkmcnt(7)
	v_mfma_f32_16x16x32_bf16 v[88:91], v[248:251], v[20:23], v[88:91]
	ds_read_b128 v[248:251], v121 offset:25792
	s_waitcnt lgkmcnt(7)
	v_mfma_f32_16x16x32_bf16 v[44:47], v[220:223], v[44:47], 0
	s_waitcnt lgkmcnt(6)
	v_mfma_f32_16x16x32_bf16 v[40:43], v[224:227], v[40:43], v[44:47]
	s_nop 4
	s_waitcnt lgkmcnt(5)
	v_mfma_f32_16x16x32_bf16 v[36:39], v[228:231], v[36:39], v[40:43]
	s_nop 2
	s_waitcnt lgkmcnt(4)
	v_mfma_f32_16x16x32_bf16 v[32:35], v[232:235], v[32:35], v[36:39]
	s_nop 2
	s_waitcnt lgkmcnt(3)
	v_mfma_f32_16x16x32_bf16 v[28:31], v[236:239], v[28:31], v[32:35]
	s_nop 2
	s_waitcnt lgkmcnt(2)
	v_mfma_f32_16x16x32_bf16 v[24:27], v[240:243], v[24:27], v[28:31]
	s_nop 2
	s_waitcnt lgkmcnt(1)
	v_mfma_f32_16x16x32_bf16 v[16:19], v[244:247], v[16:19], v[24:27]
	s_waitcnt lgkmcnt(0)
; DI void mem_attn_prompt_block(const Params& p, int item, char* smem) {
;     ...
;       st[c * 4 + m4] = a;
;       __builtin_amdgcn_sched_barrier(0);
;     }
;   }
;   float mx = -3.0e38f;
; #pragma unroll
;   for (int mt = 0; mt < 16; ++mt)
; #pragma unroll
;     for (int j = 0; j < 4; ++j) { st[mt][j] *= 0.0625f; mx = fmaxf(mx, st[mt][j]); }
;   mx = fmaxf(mx, __shfl_xor(mx, 16));
;   mx = fmaxf(mx, __shfl_xor(mx, 32));
;   float sum = 0.f;
; #pragma unroll
;   for (int mt = 0; mt < 16; ++mt)
; #pragma unroll
;     for (int j = 0; j < 4; ++j) { st[mt][j] = __expf(st[mt][j] - mx); sum += st[mt][j]; }
;   sum += __shfl_xor(sum, 16);
;   sum += __shfl_xor(sum, 32);
;   const float inv = 1.f / sum;
	v_mfma_f32_16x16x32_bf16 v[16:19], v[248:251], v[20:23], v[16:19]
	v_mul_f32_e32 v20, 0x3d800000, v0
	v_mul_f32_e32 v21, 0x3d800000, v1
	v_max3_f32 v20, v20, s37, v21
	v_mul_f32_e32 v21, 0x3d800000, v2
	v_mul_f32_e32 v22, 0x3d800000, v3
	v_max3_f32 v20, v20, v21, v22
	v_mul_f32_e32 v21, 0x3d800000, v4
	v_mul_f32_e32 v22, 0x3d800000, v5
	v_max3_f32 v20, v20, v21, v22
	v_mul_f32_e32 v21, 0x3d800000, v6
	v_mul_f32_e32 v22, 0x3d800000, v7
	v_max3_f32 v20, v20, v21, v22
	v_mul_f32_e32 v21, 0x3d800000, v8
	v_mul_f32_e32 v22, 0x3d800000, v9
	v_max3_f32 v20, v20, v21, v22
	v_mul_f32_e32 v21, 0x3d800000, v10
	v_mul_f32_e32 v22, 0x3d800000, v11
	v_max3_f32 v20, v20, v21, v22
	v_mul_f32_e32 v21, 0x3d800000, v12
	v_mul_f32_e32 v22, 0x3d800000, v13
	v_max3_f32 v20, v20, v21, v22
	v_mul_f32_e32 v21, 0x3d800000, v14
	v_mul_f32_e32 v22, 0x3d800000, v15
	v_max3_f32 v20, v20, v21, v22
	v_mul_f32_e32 v21, 0x3d800000, v48
	v_mul_f32_e32 v22, 0x3d800000, v49
	v_max3_f32 v20, v20, v21, v22
	v_mul_f32_e32 v21, 0x3d800000, v50
	v_mul_f32_e32 v22, 0x3d800000, v51
	v_max3_f32 v20, v20, v21, v22
	v_mul_f32_e32 v21, 0x3d800000, v52
	v_mul_f32_e32 v22, 0x3d800000, v53
	v_max3_f32 v20, v20, v21, v22
	v_mul_f32_e32 v21, 0x3d800000, v54
	v_mul_f32_e32 v22, 0x3d800000, v55
	v_max3_f32 v20, v20, v21, v22
	v_mul_f32_e32 v21, 0x3d800000, v56
	v_mul_f32_e32 v22, 0x3d800000, v57
	v_max3_f32 v20, v20, v21, v22
	v_mul_f32_e32 v21, 0x3d800000, v58
	v_mul_f32_e32 v22, 0x3d800000, v59
	v_max3_f32 v20, v20, v21, v22
	v_mul_f32_e32 v21, 0x3d800000, v60
	v_mul_f32_e32 v22, 0x3d800000, v61
	v_max3_f32 v20, v20, v21, v22
	v_mul_f32_e32 v21, 0x3d800000, v62
	v_mul_f32_e32 v22, 0x3d800000, v63
	v_max3_f32 v20, v20, v21, v22
	v_mul_f32_e32 v21, 0x3d800000, v64
	v_mul_f32_e32 v22, 0x3d800000, v65
	v_max3_f32 v20, v20, v21, v22
	v_mul_f32_e32 v21, 0x3d800000, v66
	v_mul_f32_e32 v22, 0x3d800000, v67
	v_max3_f32 v20, v20, v21, v22
	v_mul_f32_e32 v21, 0x3d800000, v68
	v_mul_f32_e32 v22, 0x3d800000, v69
	v_max3_f32 v20, v20, v21, v22
	v_mul_f32_e32 v21, 0x3d800000, v70
	v_mul_f32_e32 v22, 0x3d800000, v71
	v_max3_f32 v20, v20, v21, v22
	v_mul_f32_e32 v21, 0x3d800000, v72
	v_mul_f32_e32 v22, 0x3d800000, v73
	v_max3_f32 v20, v20, v21, v22
	v_mul_f32_e32 v21, 0x3d800000, v74
	v_mul_f32_e32 v22, 0x3d800000, v75
	v_max3_f32 v20, v20, v21, v22
	v_mul_f32_e32 v21, 0x3d800000, v76
	v_mul_f32_e32 v22, 0x3d800000, v77
	v_max3_f32 v20, v20, v21, v22
	v_mul_f32_e32 v21, 0x3d800000, v78
	v_mul_f32_e32 v22, 0x3d800000, v79
	v_max3_f32 v20, v20, v21, v22
	v_mul_f32_e32 v21, 0x3d800000, v80
	v_mul_f32_e32 v22, 0x3d800000, v81
	v_max3_f32 v20, v20, v21, v22
	v_mul_f32_e32 v21, 0x3d800000, v82
	v_mul_f32_e32 v22, 0x3d800000, v83
	v_max3_f32 v20, v20, v21, v22
	v_mul_f32_e32 v21, 0x3d800000, v84
	v_mul_f32_e32 v22, 0x3d800000, v85
	v_max3_f32 v20, v20, v21, v22
	v_mul_f32_e32 v21, 0x3d800000, v86
	v_mul_f32_e32 v22, 0x3d800000, v87
	v_max3_f32 v20, v20, v21, v22
	v_mul_f32_e32 v21, 0x3d800000, v88
	v_mul_f32_e32 v22, 0x3d800000, v89
	v_max3_f32 v20, v20, v21, v22
	v_mul_f32_e32 v21, 0x3d800000, v90
	v_mul_f32_e32 v22, 0x3d800000, v91
	v_max3_f32 v20, v20, v21, v22
	v_mul_f32_e32 v21, 0x3d800000, v16
	v_mul_f32_e32 v22, 0x3d800000, v17
	v_max3_f32 v20, v20, v21, v22
	v_mul_f32_e32 v21, 0x3d800000, v18
	v_mul_f32_e32 v22, 0x3d800000, v19
	v_cmp_lt_i32_e32 vcc, v152, v153
	v_max3_f32 v20, v20, v21, v22
	s_nop 0
	v_cndmask_b32_e32 v21, v128, v152, vcc
	v_lshlrev_b32_e32 v21, 2, v21
	ds_bpermute_b32 v22, v21, v20
	v_cmp_lt_i32_e32 vcc, v154, v153
	s_waitcnt lgkmcnt(0)
	v_max_f32_e32 v22, v22, v22
	v_max_f32_e32 v20, v20, v22
	v_cndmask_b32_e32 v22, v128, v154, vcc
	v_lshlrev_b32_e32 v22, 2, v22
	ds_bpermute_b32 v23, v22, v20
	s_waitcnt lgkmcnt(0)
	v_max_f32_e32 v23, v23, v23
	v_max_f32_e32 v20, v20, v23
	v_fma_f32 v0, v0, s36, -v20
	v_mul_f32_e32 v0, 0x3fb8aa3b, v0
	v_fma_f32 v1, v1, s36, -v20
	v_exp_f32_e32 v0, v0
	v_mul_f32_e32 v1, 0x3fb8aa3b, v1
	v_fma_f32 v2, v2, s36, -v20
	v_exp_f32_e32 v1, v1
	v_mul_f32_e32 v2, 0x3fb8aa3b, v2
	v_fma_f32 v3, v3, s36, -v20
	v_exp_f32_e32 v2, v2
	v_mul_f32_e32 v3, 0x3fb8aa3b, v3
	v_fma_f32 v4, v4, s36, -v20
	v_exp_f32_e32 v3, v3
	v_mul_f32_e32 v4, 0x3fb8aa3b, v4
	v_fma_f32 v5, v5, s36, -v20
	v_add_f32_e32 v23, 0, v0
	v_exp_f32_e32 v4, v4
	v_mul_f32_e32 v5, 0x3fb8aa3b, v5
	v_fma_f32 v6, v6, s36, -v20
	v_add_f32_e32 v23, v1, v23
	v_exp_f32_e32 v5, v5
	v_mul_f32_e32 v6, 0x3fb8aa3b, v6
	v_fma_f32 v7, v7, s36, -v20
	v_add_f32_e32 v23, v2, v23
	v_exp_f32_e32 v6, v6
	v_mul_f32_e32 v7, 0x3fb8aa3b, v7
	v_fma_f32 v8, v8, s36, -v20
	v_add_f32_e32 v23, v3, v23
	v_exp_f32_e32 v7, v7
	v_mul_f32_e32 v8, 0x3fb8aa3b, v8
	v_fma_f32 v9, v9, s36, -v20
	v_add_f32_e32 v23, v4, v23
	v_exp_f32_e32 v8, v8
	v_mul_f32_e32 v9, 0x3fb8aa3b, v9
	v_fma_f32 v10, v10, s36, -v20
	v_add_f32_e32 v23, v5, v23
	v_exp_f32_e32 v9, v9
	v_mul_f32_e32 v10, 0x3fb8aa3b, v10
	v_fma_f32 v11, v11, s36, -v20
	v_add_f32_e32 v23, v6, v23
	v_exp_f32_e32 v10, v10
	v_mul_f32_e32 v11, 0x3fb8aa3b, v11
	v_fma_f32 v12, v12, s36, -v20
	v_add_f32_e32 v23, v7, v23
	v_exp_f32_e32 v11, v11
	v_mul_f32_e32 v12, 0x3fb8aa3b, v12
	v_fma_f32 v13, v13, s36, -v20
	v_add_f32_e32 v23, v8, v23
	v_exp_f32_e32 v12, v12
	v_mul_f32_e32 v13, 0x3fb8aa3b, v13
	v_fma_f32 v14, v14, s36, -v20
	v_add_f32_e32 v23, v9, v23
	v_exp_f32_e32 v13, v13
	v_mul_f32_e32 v14, 0x3fb8aa3b, v14
	v_fma_f32 v15, v15, s36, -v20
	v_add_f32_e32 v23, v10, v23
	v_exp_f32_e32 v14, v14
	v_mul_f32_e32 v15, 0x3fb8aa3b, v15
	v_fma_f32 v24, v48, s36, -v20
	v_add_f32_e32 v23, v11, v23
	v_exp_f32_e32 v15, v15
	v_mul_f32_e32 v24, 0x3fb8aa3b, v24
	v_fma_f32 v25, v49, s36, -v20
	v_add_f32_e32 v23, v12, v23
; DI void mem_attn_prompt_block(const Params& p, int item, char* smem) {
;     ...
;   float sum = 0.f;
; #pragma unroll
;   for (int mt = 0; mt < 16; ++mt)
; #pragma unroll
;     for (int j = 0; j < 4; ++j) { st[mt][j] = __expf(st[mt][j] - mx); sum += st[mt][j]; }
;   sum += __shfl_xor(sum, 16);
;   sum += __shfl_xor(sum, 32);
;   const float inv = 1.f / sum;
;   bf16x8 pf[8];
; #pragma unroll
;   for (int k2 = 0; k2 < 8; ++k2) pf[k2] = pack8(st[2 * k2], st[2 * k2 + 1]);
	v_exp_f32_e32 v24, v24
	v_mul_f32_e32 v25, 0x3fb8aa3b, v25
	v_fma_f32 v26, v50, s36, -v20
	v_add_f32_e32 v23, v13, v23
	v_exp_f32_e32 v25, v25
	v_mul_f32_e32 v26, 0x3fb8aa3b, v26
	v_fma_f32 v27, v51, s36, -v20
	v_add_f32_e32 v23, v14, v23
	v_exp_f32_e32 v26, v26
	v_mul_f32_e32 v27, 0x3fb8aa3b, v27
	v_fma_f32 v28, v52, s36, -v20
	v_add_f32_e32 v23, v15, v23
	v_exp_f32_e32 v27, v27
	v_mul_f32_e32 v28, 0x3fb8aa3b, v28
	v_fma_f32 v29, v53, s36, -v20
	v_add_f32_e32 v23, v24, v23
	v_exp_f32_e32 v28, v28
	v_mul_f32_e32 v29, 0x3fb8aa3b, v29
	v_fma_f32 v30, v54, s36, -v20
	v_add_f32_e32 v23, v25, v23
	v_exp_f32_e32 v29, v29
	v_mul_f32_e32 v30, 0x3fb8aa3b, v30
	v_fma_f32 v31, v55, s36, -v20
	v_add_f32_e32 v23, v26, v23
	v_exp_f32_e32 v30, v30
	v_mul_f32_e32 v31, 0x3fb8aa3b, v31
	v_fma_f32 v32, v56, s36, -v20
	v_add_f32_e32 v23, v27, v23
	v_exp_f32_e32 v31, v31
	v_mul_f32_e32 v32, 0x3fb8aa3b, v32
	v_fma_f32 v33, v57, s36, -v20
	v_add_f32_e32 v23, v28, v23
	v_exp_f32_e32 v32, v32
	v_mul_f32_e32 v33, 0x3fb8aa3b, v33
	v_fma_f32 v34, v58, s36, -v20
	v_add_f32_e32 v23, v29, v23
	v_exp_f32_e32 v33, v33
	v_mul_f32_e32 v34, 0x3fb8aa3b, v34
	v_fma_f32 v35, v59, s36, -v20
	v_add_f32_e32 v23, v30, v23
	v_exp_f32_e32 v34, v34
	v_mul_f32_e32 v35, 0x3fb8aa3b, v35
	v_fma_f32 v36, v60, s36, -v20
	v_add_f32_e32 v23, v31, v23
	v_exp_f32_e32 v35, v35
	v_mul_f32_e32 v36, 0x3fb8aa3b, v36
	v_fma_f32 v37, v61, s36, -v20
	v_add_f32_e32 v23, v32, v23
	v_exp_f32_e32 v36, v36
	v_mul_f32_e32 v37, 0x3fb8aa3b, v37
	v_fma_f32 v38, v62, s36, -v20
	v_add_f32_e32 v23, v33, v23
	v_exp_f32_e32 v37, v37
	v_mul_f32_e32 v38, 0x3fb8aa3b, v38
	v_fma_f32 v39, v63, s36, -v20
	v_add_f32_e32 v23, v34, v23
	v_exp_f32_e32 v38, v38
	v_mul_f32_e32 v39, 0x3fb8aa3b, v39
	v_fma_f32 v40, v64, s36, -v20
	v_add_f32_e32 v23, v35, v23
	v_exp_f32_e32 v39, v39
	v_mul_f32_e32 v40, 0x3fb8aa3b, v40
	v_fma_f32 v41, v65, s36, -v20
	v_add_f32_e32 v23, v36, v23
	v_exp_f32_e32 v40, v40
	v_mul_f32_e32 v41, 0x3fb8aa3b, v41
	v_fma_f32 v42, v66, s36, -v20
	v_add_f32_e32 v23, v37, v23
	v_exp_f32_e32 v41, v41
	v_mul_f32_e32 v42, 0x3fb8aa3b, v42
	v_fma_f32 v43, v67, s36, -v20
	v_add_f32_e32 v23, v38, v23
	v_exp_f32_e32 v42, v42
	v_mul_f32_e32 v43, 0x3fb8aa3b, v43
	v_fma_f32 v44, v68, s36, -v20
	v_add_f32_e32 v23, v39, v23
	v_exp_f32_e32 v43, v43
	v_mul_f32_e32 v44, 0x3fb8aa3b, v44
	v_fma_f32 v45, v69, s36, -v20
	v_add_f32_e32 v23, v40, v23
	v_exp_f32_e32 v44, v44
	v_mul_f32_e32 v45, 0x3fb8aa3b, v45
	v_fma_f32 v46, v70, s36, -v20
	v_add_f32_e32 v23, v41, v23
	v_exp_f32_e32 v45, v45
	v_mul_f32_e32 v46, 0x3fb8aa3b, v46
	v_fma_f32 v47, v71, s36, -v20
	v_add_f32_e32 v23, v42, v23
	v_exp_f32_e32 v46, v46
	v_mul_f32_e32 v47, 0x3fb8aa3b, v47
	v_fma_f32 v48, v72, s36, -v20
	v_add_f32_e32 v23, v43, v23
	v_exp_f32_e32 v47, v47
	v_mul_f32_e32 v48, 0x3fb8aa3b, v48
	v_fma_f32 v49, v73, s36, -v20
	v_add_f32_e32 v23, v44, v23
	v_exp_f32_e32 v48, v48
	v_mul_f32_e32 v49, 0x3fb8aa3b, v49
	v_fma_f32 v50, v74, s36, -v20
	v_add_f32_e32 v23, v45, v23
	v_exp_f32_e32 v49, v49
	v_mul_f32_e32 v50, 0x3fb8aa3b, v50
	v_fma_f32 v51, v75, s36, -v20
	v_add_f32_e32 v23, v46, v23
	v_exp_f32_e32 v50, v50
	v_mul_f32_e32 v51, 0x3fb8aa3b, v51
	v_fma_f32 v52, v76, s36, -v20
	v_add_f32_e32 v23, v47, v23
	v_exp_f32_e32 v51, v51
	v_mul_f32_e32 v52, 0x3fb8aa3b, v52
	v_fma_f32 v53, v77, s36, -v20
	v_add_f32_e32 v23, v48, v23
	v_exp_f32_e32 v52, v52
	v_mul_f32_e32 v53, 0x3fb8aa3b, v53
	v_fma_f32 v54, v78, s36, -v20
	v_add_f32_e32 v23, v49, v23
	v_exp_f32_e32 v53, v53
	v_mul_f32_e32 v54, 0x3fb8aa3b, v54
	v_fma_f32 v55, v79, s36, -v20
	v_add_f32_e32 v23, v50, v23
	v_exp_f32_e32 v54, v54
	v_mul_f32_e32 v55, 0x3fb8aa3b, v55
	v_fma_f32 v56, v80, s36, -v20
	v_add_f32_e32 v23, v51, v23
	v_exp_f32_e32 v55, v55
	v_mul_f32_e32 v56, 0x3fb8aa3b, v56
	v_fma_f32 v57, v81, s36, -v20
	v_add_f32_e32 v23, v52, v23
	v_exp_f32_e32 v56, v56
	v_mul_f32_e32 v57, 0x3fb8aa3b, v57
	v_fma_f32 v58, v82, s36, -v20
	v_add_f32_e32 v23, v53, v23
	v_exp_f32_e32 v57, v57
	v_mul_f32_e32 v58, 0x3fb8aa3b, v58
	v_fma_f32 v59, v83, s36, -v20
	v_add_f32_e32 v23, v54, v23
	v_exp_f32_e32 v58, v58
	v_mul_f32_e32 v59, 0x3fb8aa3b, v59
	v_fma_f32 v60, v84, s36, -v20
	v_add_f32_e32 v23, v55, v23
	v_exp_f32_e32 v59, v59
	v_mul_f32_e32 v60, 0x3fb8aa3b, v60
	v_fma_f32 v61, v85, s36, -v20
	v_add_f32_e32 v23, v56, v23
	v_exp_f32_e32 v60, v60
	v_mul_f32_e32 v61, 0x3fb8aa3b, v61
	v_fma_f32 v62, v86, s36, -v20
	v_add_f32_e32 v23, v57, v23
	v_exp_f32_e32 v61, v61
	v_mul_f32_e32 v62, 0x3fb8aa3b, v62
	v_fma_f32 v63, v87, s36, -v20
	v_add_f32_e32 v23, v58, v23
	v_exp_f32_e32 v62, v62
	v_mul_f32_e32 v63, 0x3fb8aa3b, v63
	v_fma_f32 v64, v88, s36, -v20
	v_add_f32_e32 v23, v59, v23
	v_exp_f32_e32 v63, v63
	v_mul_f32_e32 v64, 0x3fb8aa3b, v64
	v_fma_f32 v65, v89, s36, -v20
	v_fma_f32 v16, v16, s36, -v20
	v_add_f32_e32 v23, v60, v23
	v_exp_f32_e32 v64, v64
	v_mul_f32_e32 v65, 0x3fb8aa3b, v65
	v_fma_f32 v66, v90, s36, -v20
	v_mul_f32_e32 v16, 0x3fb8aa3b, v16
	v_add_f32_e32 v23, v61, v23
	v_exp_f32_e32 v65, v65
	v_mul_f32_e32 v66, 0x3fb8aa3b, v66
	v_fma_f32 v67, v91, s36, -v20
	v_exp_f32_e32 v68, v16
	v_fma_f32 v16, v17, s36, -v20
	v_add_f32_e32 v23, v62, v23
	v_exp_f32_e32 v66, v66
	v_mul_f32_e32 v67, 0x3fb8aa3b, v67
	v_mul_f32_e32 v16, 0x3fb8aa3b, v16
	v_add_f32_e32 v23, v63, v23
	v_exp_f32_e32 v67, v67
	v_exp_f32_e32 v69, v16
	v_fma_f32 v16, v18, s36, -v20
	v_add_f32_e32 v23, v64, v23
	v_mul_f32_e32 v16, 0x3fb8aa3b, v16
	v_add_f32_e32 v23, v65, v23
	v_exp_f32_e32 v70, v16
	v_fma_f32 v16, v19, s36, -v20
	v_add_f32_e32 v23, v66, v23
	v_mul_f32_e32 v16, 0x3fb8aa3b, v16
	v_add_f32_e32 v23, v67, v23
	v_exp_f32_e32 v71, v16
	v_add_f32_e32 v16, v68, v23
	v_add_f32_e32 v16, v69, v16
	v_add_f32_e32 v16, v70, v16
	v_add_f32_e32 v16, v71, v16
	ds_bpermute_b32 v17, v21, v16
	v_bfe_u32 v18, v3, 16, 1
	v_bfe_u32 v19, v1, 16, 1
	v_add3_u32 v19, v1, v19, s38
	v_add3_u32 v1, v3, v18, s38
	s_waitcnt lgkmcnt(0)
; DI u16 f2bf(float x) { unsigned u = __float_as_uint(x); u += 0x7fffu + ((u >> 16) & 1u); return (u16)(u >> 16); }
; DI float bf2f(u16 h) { return __uint_as_float(((unsigned)h) << 16); }
; DI unsigned pack2(float a, float b) { return (unsigned)f2bf(a) | ((unsigned)f2bf(b) << 16); }
; DI float bflo(unsigned d) { return __uint_as_float(d << 16); }
; DI float bfhi(unsigned d) { return __uint_as_float(d & 0xffff0000u); }
; DI bf16x8 pack8(f32x4 a, f32x4 b) {
;   uint4 r; r.x = pack2(a[0], a[1]); r.y = pack2(a[2], a[3]); r.z = pack2(b[0], b[1]); r.w = pack2(b[2], b[3]);
;   return __builtin_bit_cast(bf16x8, r);
; }
; DI void mem_attn_prompt_block(const Params& p, int item, char* smem) {
;     ...
;   sum += __shfl_xor(sum, 16);
;   sum += __shfl_xor(sum, 32);
;   const float inv = 1.f / sum;
;   bf16x8 pf[8];
; #pragma unroll
;   for (int k2 = 0; k2 < 8; ++k2) pf[k2] = pack8(st[2 * k2], st[2 * k2 + 1]);
;   const u16* vtp = G(p.VTf) + (size_t)bh * 65536;
	v_add_f32_e32 v16, v16, v17
	ds_bpermute_b32 v17, v22, v16
	v_bfe_u32 v18, v6, 16, 1
	v_add3_u32 v6, v6, v18, s38
	v_bfe_u32 v18, v36, 16, 1
	v_add3_u32 v18, v36, v18, s38
	s_waitcnt lgkmcnt(0)
	v_add_f32_e32 v72, v16, v17
	v_bfe_u32 v16, v7, 16, 1
	v_bfe_u32 v17, v5, 16, 1
	v_add3_u32 v5, v5, v17, s38
	v_add3_u32 v3, v7, v16, s38
	v_bfe_u32 v16, v2, 16, 1
	v_bfe_u32 v17, v4, 16, 1
	v_bfe_u32 v7, v0, 16, 1
	v_add3_u32 v4, v4, v17, s38
	v_add3_u32 v2, v2, v16, s38
	v_add3_u32 v0, v0, v7, s38
	v_lshrrev_b32_e32 v7, 16, v2
	v_lshrrev_b32_e32 v2, 16, v4
	v_lshrrev_b32_e32 v4, 16, v6
	v_and_or_b32 v2, v5, s39, v2
	v_and_or_b32 v1, v1, s39, v7
	v_bfe_u32 v5, v13, 16, 1
	v_bfe_u32 v6, v11, 16, 1
	v_bfe_u32 v7, v9, 16, 1
	v_add3_u32 v9, v9, v7, s38
	v_add3_u32 v11, v11, v6, s38
	v_add3_u32 v5, v13, v5, s38
	v_bfe_u32 v6, v8, 16, 1
	v_bfe_u32 v7, v10, 16, 1
	v_bfe_u32 v13, v12, 16, 1
	v_and_or_b32 v3, v3, s39, v4
	v_bfe_u32 v4, v15, 16, 1
	v_add3_u32 v12, v12, v13, s38
	v_add3_u32 v7, v10, v7, s38
	v_add3_u32 v6, v8, v6, s38
	v_add3_u32 v4, v15, v4, s38
	v_bfe_u32 v15, v14, 16, 1
	v_lshrrev_b32_e32 v8, 16, v6
	v_lshrrev_b32_e32 v10, 16, v7
	v_lshrrev_b32_e32 v6, 16, v12
	v_add3_u32 v14, v14, v15, s38
	v_and_or_b32 v6, v5, s39, v6
	v_and_or_b32 v5, v11, s39, v10
	v_bfe_u32 v10, v27, 16, 1
	v_bfe_u32 v11, v25, 16, 1
	v_lshrrev_b32_e32 v7, 16, v14
	v_add3_u32 v12, v25, v11, s38
	v_add3_u32 v13, v27, v10, s38
	v_bfe_u32 v10, v24, 16, 1
	v_bfe_u32 v11, v26, 16, 1
	v_bfe_u32 v14, v28, 16, 1
	v_bfe_u32 v15, v30, 16, 1
	v_and_or_b32 v7, v4, s39, v7
	v_and_or_b32 v4, v9, s39, v8
	v_bfe_u32 v8, v31, 16, 1
	v_bfe_u32 v9, v29, 16, 1
	v_add3_u32 v15, v30, v15, s38
	v_add3_u32 v14, v28, v14, s38
	v_add3_u32 v11, v26, v11, s38
	v_add3_u32 v10, v24, v10, s38
	v_lshrrev_b32_e32 v0, 16, v0
	v_add3_u32 v9, v29, v9, s38
	v_add3_u32 v8, v31, v8, s38
	v_lshrrev_b32_e32 v16, 16, v10
	v_lshrrev_b32_e32 v17, 16, v11
	v_lshrrev_b32_e32 v10, 16, v14
	v_lshrrev_b32_e32 v11, 16, v15
	v_bfe_u32 v14, v35, 16, 1
	v_bfe_u32 v15, v33, 16, 1
	v_and_or_b32 v0, v19, s39, v0
	v_and_or_b32 v11, v8, s39, v11
	v_and_or_b32 v10, v9, s39, v10
	v_and_or_b32 v9, v13, s39, v17
	v_and_or_b32 v8, v12, s39, v16
	v_add3_u32 v16, v33, v15, s38
	v_add3_u32 v17, v35, v14, s38
	v_bfe_u32 v14, v32, 16, 1
	v_bfe_u32 v15, v34, 16, 1
	v_bfe_u32 v19, v38, 16, 1
	v_bfe_u32 v12, v39, 16, 1
	v_bfe_u32 v13, v37, 16, 1
	v_add3_u32 v19, v38, v19, s38
	v_add3_u32 v15, v34, v15, s38
	v_add3_u32 v14, v32, v14, s38
	v_add3_u32 v13, v37, v13, s38
	v_add3_u32 v12, v39, v12, s38
	v_lshrrev_b32_e32 v20, 16, v14
	v_lshrrev_b32_e32 v21, 16, v15
	v_lshrrev_b32_e32 v14, 16, v18
	v_lshrrev_b32_e32 v15, 16, v19
	v_bfe_u32 v18, v43, 16, 1
	v_bfe_u32 v19, v41, 16, 1
	v_and_or_b32 v15, v12, s39, v15
	v_and_or_b32 v14, v13, s39, v14
	v_and_or_b32 v13, v17, s39, v21
	v_and_or_b32 v12, v16, s39, v20
	v_add3_u32 v20, v41, v19, s38
	v_add3_u32 v21, v43, v18, s38
	v_bfe_u32 v18, v40, 16, 1
	v_bfe_u32 v19, v42, 16, 1
	v_bfe_u32 v22, v44, 16, 1
	v_bfe_u32 v23, v46, 16, 1
	v_bfe_u32 v16, v47, 16, 1
	v_bfe_u32 v17, v45, 16, 1
	v_add3_u32 v23, v46, v23, s38
	v_add3_u32 v22, v44, v22, s38
	v_add3_u32 v19, v42, v19, s38
	v_add3_u32 v18, v40, v18, s38
	v_add3_u32 v17, v45, v17, s38
	v_add3_u32 v16, v47, v16, s38
	v_lshrrev_b32_e32 v24, 16, v18
	v_lshrrev_b32_e32 v25, 16, v19
	v_lshrrev_b32_e32 v18, 16, v22
	v_lshrrev_b32_e32 v19, 16, v23
	v_bfe_u32 v22, v51, 16, 1
	v_bfe_u32 v23, v49, 16, 1
	v_and_or_b32 v19, v16, s39, v19
	v_and_or_b32 v18, v17, s39, v18
	v_and_or_b32 v17, v21, s39, v25
	v_and_or_b32 v16, v20, s39, v24
	v_add3_u32 v24, v49, v23, s38
	v_add3_u32 v25, v51, v22, s38
	v_bfe_u32 v22, v48, 16, 1
	v_bfe_u32 v23, v50, 16, 1
	v_bfe_u32 v26, v52, 16, 1
	v_bfe_u32 v27, v54, 16, 1
	v_bfe_u32 v20, v55, 16, 1
	v_bfe_u32 v21, v53, 16, 1
	v_add3_u32 v27, v54, v27, s38
	v_add3_u32 v26, v52, v26, s38
	v_add3_u32 v23, v50, v23, s38
	v_add3_u32 v22, v48, v22, s38
	v_add3_u32 v21, v53, v21, s38
	v_add3_u32 v20, v55, v20, s38
	v_lshrrev_b32_e32 v28, 16, v22
	v_lshrrev_b32_e32 v29, 16, v23
	v_lshrrev_b32_e32 v22, 16, v26
	v_lshrrev_b32_e32 v23, 16, v27
	v_bfe_u32 v26, v59, 16, 1
	v_bfe_u32 v27, v57, 16, 1
	v_and_or_b32 v23, v20, s39, v23
	v_and_or_b32 v22, v21, s39, v22
	v_and_or_b32 v21, v25, s39, v29
	v_and_or_b32 v20, v24, s39, v28
	v_add3_u32 v28, v57, v27, s38
	v_add3_u32 v29, v59, v26, s38
	v_bfe_u32 v26, v56, 16, 1
	v_bfe_u32 v27, v58, 16, 1
	v_bfe_u32 v30, v60, 16, 1
	v_bfe_u32 v31, v62, 16, 1
	v_bfe_u32 v24, v63, 16, 1
	v_bfe_u32 v25, v61, 16, 1
	v_add3_u32 v31, v62, v31, s38
	v_add3_u32 v30, v60, v30, s38
	v_add3_u32 v27, v58, v27, s38
	v_add3_u32 v26, v56, v26, s38
	v_div_scale_f32 v38, s[24:25], v72, v72, 1.0
	v_add3_u32 v25, v61, v25, s38
	v_add3_u32 v24, v63, v24, s38
	v_lshrrev_b32_e32 v32, 16, v26
	v_lshrrev_b32_e32 v33, 16, v27
	v_lshrrev_b32_e32 v26, 16, v30
	v_lshrrev_b32_e32 v27, 16, v31
	v_bfe_u32 v30, v67, 16, 1
	v_bfe_u32 v31, v65, 16, 1
	v_rcp_f32_e32 v39, v38
	v_and_or_b32 v27, v24, s39, v27
	v_and_or_b32 v26, v25, s39, v26
	v_and_or_b32 v25, v29, s39, v33
	v_and_or_b32 v24, v28, s39, v32
	v_add3_u32 v32, v65, v31, s38
	v_add3_u32 v33, v67, v30, s38
	v_bfe_u32 v30, v64, 16, 1
	v_bfe_u32 v31, v66, 16, 1
	v_bfe_u32 v35, v70, 16, 1
	v_bfe_u32 v28, v71, 16, 1
	v_add3_u32 v35, v70, v35, s38
	v_add3_u32 v31, v66, v31, s38
	v_add3_u32 v30, v64, v30, s38
	v_add3_u32 v28, v71, v28, s38
	v_bfe_u32 v34, v68, 16, 1
	v_lshrrev_b32_e32 v36, 16, v30
	v_lshrrev_b32_e32 v37, 16, v31
	v_lshrrev_b32_e32 v31, 16, v35
	v_bfe_u32 v29, v69, 16, 1
	v_add3_u32 v34, v68, v34, s38
	v_and_or_b32 v31, v28, s39, v31
	v_and_or_b32 v28, v32, s39, v36
	v_fma_f32 v32, -v38, v39, 1.0
	v_add3_u32 v29, v69, v29, s38
	v_lshrrev_b32_e32 v30, 16, v34
	v_fmac_f32_e32 v39, v32, v39
	v_div_scale_f32 v32, vcc, 1.0, v72, 1.0
	v_and_or_b32 v30, v29, s39, v30
	v_and_or_b32 v29, v33, s39, v37
	v_mul_f32_e32 v33, v32, v39
	v_fma_f32 v34, -v38, v33, v32
	v_fmac_f32_e32 v33, v34, v39
	ds_read_b64 v[34:35], v148
	v_fma_f32 v32, -v38, v33, v32
	v_div_fmas_f32 v32, v32, v39, v33
	v_div_fixup_f32 v32, v32, v72, 1.0
	v_mov_b32_e32 v33, v32
	s_waitcnt lgkmcnt(0)
	v_lshl_add_u64 v[34:35], v[34:35], 0, s[0:1]
	v_lshl_add_u64 v[34:35], v[34:35], 0, v[140:141]
	s_mov_b64 s[24:25], 0
	v_mov_b64_e32 v[36:37], v[94:95]
; #define MFMA(a, b, c) __builtin_amdgcn_mfma_f32_16x16x32_bf16((a), (b), (c), 0, 0, 0)
; DI unsigned pack2(float a, float b) { return (unsigned)f2bf(a) | ((unsigned)f2bf(b) << 16); }
; DI void mem_attn_prompt_block(const Params& p, int item, char* smem) {
;     ...
;   const u16* vtp = G(p.VTf) + (size_t)bh * 65536;
; #pragma unroll 1
;   for (int c = 0; c < 4; ++c) {
;     __syncthreads();
; #pragma unroll
;     for (int i = 0; i < 8; ++i) {
;       const int idx = tid + 256 * i;
;       *(bf16x8*)&sK[idx * 8] = *(gb8p)((gu16p)vtp + (size_t)c * 16384 + idx * 8);
;     }
;     __syncthreads();
; #pragma unroll
;     for (int n4 = 0; n4 < 4; ++n4) {
;       f32x4 o = (f32x4){0.f, 0.f, 0.f, 0.f};
; #pragma unroll
;       for (int k2 = 0; k2 < 8; ++k2) o = MFMA(*(const bf16x8*)&sK[((n4 * 8 + k2) * 64 + lane) * 8], pf[k2], o);
;       uint2 ov; ov.x = pack2(o[0] * inv, o[1] * inv); ov.y = pack2(o[2] * inv, o[3] * inv);
;       *(uint2*)&G(p.attn)[(size_t)(row0 + r) * 1024 + h * 256 + (c * 4 + n4) * 16 + kg * 4] = ov;
;       __builtin_amdgcn_sched_barrier(0);
;     }
;   }
.LBB0_889:
	v_lshl_add_u64 v[62:63], v[34:35], 0, s[24:25]
	v_add_co_u32_e32 v42, vcc, 0x1000, v62
	s_nop 1
	v_addc_co_u32_e32 v43, vcc, 0, v63, vcc
	v_add_co_u32_e32 v46, vcc, 0x2000, v62
	s_barrier
	s_nop 0
	v_addc_co_u32_e32 v47, vcc, 0, v63, vcc
	v_add_co_u32_e32 v50, vcc, 0x3000, v62
	s_nop 1
	v_addc_co_u32_e32 v51, vcc, 0, v63, vcc
	v_add_co_u32_e32 v54, vcc, s26, v62
	global_load_dwordx4 v[38:41], v[62:63], off
	s_nop 0
	global_load_dwordx4 v[42:45], v[42:43], off
	v_addc_co_u32_e32 v55, vcc, 0, v63, vcc
	v_add_co_u32_e32 v58, vcc, 0x5000, v62
	global_load_dwordx4 v[46:49], v[46:47], off
	s_nop 0
	global_load_dwordx4 v[50:53], v[50:51], off
	v_addc_co_u32_e32 v59, vcc, 0, v63, vcc
	v_add_co_u32_e32 v64, vcc, 0x6000, v62
	global_load_dwordx4 v[54:57], v[54:55], off
	s_nop 0
	global_load_dwordx4 v[58:61], v[58:59], off
	v_addc_co_u32_e32 v65, vcc, 0, v63, vcc
	v_add_co_u32_e32 v66, vcc, 0x7000, v62
	s_nop 1
	v_addc_co_u32_e32 v67, vcc, 0, v63, vcc
	global_load_dwordx4 v[62:65], v[64:65], off
	s_nop 0
	global_load_dwordx4 v[66:69], v[66:67], off
	s_waitcnt vmcnt(0)
	ds_write_b128 v122, v[38:41]
	s_waitcnt vmcnt(6)
	ds_write_b128 v122, v[42:45] offset:4096
	s_waitcnt vmcnt(5)
	ds_write_b128 v122, v[46:49] offset:8192
	s_waitcnt vmcnt(4)
	ds_write_b128 v122, v[50:53] offset:12288
	s_waitcnt vmcnt(3)
	ds_write_b128 v122, v[54:57] offset:16384
	s_waitcnt vmcnt(2)
	ds_write_b128 v122, v[58:61] offset:20480
	s_waitcnt vmcnt(1)
	ds_write_b128 v122, v[62:65] offset:24576
	s_waitcnt vmcnt(0)
	ds_write_b128 v122, v[66:69] offset:28672
	s_waitcnt lgkmcnt(0)
	s_barrier
	ds_read_b128 v[220:223], v197
	ds_read_b128 v[224:227], v197 offset:1024
	ds_read_b128 v[228:231], v197 offset:2048
	ds_read_b128 v[232:235], v197 offset:3072
	ds_read_b128 v[236:239], v197 offset:4096
	ds_read_b128 v[240:243], v197 offset:5120
	ds_read_b128 v[244:247], v197 offset:6144
	ds_read_b128 v[248:251], v197 offset:7168
	s_waitcnt lgkmcnt(7)
	v_mfma_f32_16x16x32_bf16 v[38:41], v[220:223], v[0:3], 0
	ds_read_b128 v[220:223], v197 offset:8192
	s_waitcnt lgkmcnt(7)
	v_mfma_f32_16x16x32_bf16 v[38:41], v[224:227], v[4:7], v[38:41]
	ds_read_b128 v[224:227], v197 offset:9216
	s_waitcnt lgkmcnt(7)
	v_mfma_f32_16x16x32_bf16 v[38:41], v[228:231], v[8:11], v[38:41]
	ds_read_b128 v[228:231], v197 offset:10240
	s_waitcnt lgkmcnt(7)
	v_mfma_f32_16x16x32_bf16 v[38:41], v[232:235], v[12:15], v[38:41]
	ds_read_b128 v[232:235], v197 offset:11264
	s_waitcnt lgkmcnt(7)
	v_mfma_f32_16x16x32_bf16 v[38:41], v[236:239], v[16:19], v[38:41]
	ds_read_b128 v[236:239], v197 offset:12288
	s_waitcnt lgkmcnt(7)
	v_mfma_f32_16x16x32_bf16 v[38:41], v[240:243], v[20:23], v[38:41]
	ds_read_b128 v[240:243], v197 offset:13312
	s_waitcnt lgkmcnt(7)
	v_mfma_f32_16x16x32_bf16 v[38:41], v[244:247], v[24:27], v[38:41]
	ds_read_b128 v[244:247], v197 offset:14336
	ds_read_b64 v[42:43], v149
	s_waitcnt lgkmcnt(0)
	v_lshl_add_u64 v[42:43], v[42:43], 0, v[36:37]
	s_waitcnt lgkmcnt(8)
	v_mfma_f32_16x16x32_bf16 v[38:41], v[248:251], v[28:31], v[38:41]
	ds_read_b128 v[248:251], v197 offset:15360
	s_nop 7
	v_mov_b32_e32 v45, v40
	v_mov_b32_e32 v40, v39
	v_mov_b32_e32 v44, v38
	v_pk_mul_f32 v[40:41], v[32:33], v[40:41]
	v_pk_mul_f32 v[38:39], v[32:33], v[44:45]
	v_and_b32_sdwa v47, v40, v155 dst_sel:DWORD dst_unused:UNUSED_PAD src0_sel:WORD_1 src1_sel:DWORD
	v_and_b32_sdwa v45, v38, v155 dst_sel:DWORD dst_unused:UNUSED_PAD src0_sel:WORD_1 src1_sel:DWORD
	v_and_b32_sdwa v46, v41, v155 dst_sel:DWORD dst_unused:UNUSED_PAD src0_sel:WORD_1 src1_sel:DWORD
	v_add3_u32 v40, v40, v47, s38
	v_and_b32_sdwa v44, v39, v155 dst_sel:DWORD dst_unused:UNUSED_PAD src0_sel:WORD_1 src1_sel:DWORD
	v_add3_u32 v38, v38, v45, s38
	v_add3_u32 v41, v41, v46, s38
	v_and_b32_e32 v40, 0xffff0000, v40
	v_add3_u32 v39, v39, v44, s38
	v_and_b32_e32 v41, 0xffff0000, v41
	v_or_b32_sdwa v38, v40, v38 dst_sel:DWORD dst_unused:UNUSED_PAD src0_sel:DWORD src1_sel:WORD_1
	v_add_co_u32_e32 v40, vcc, s44, v42
	v_or_b32_sdwa v39, v41, v39 dst_sel:DWORD dst_unused:UNUSED_PAD src0_sel:DWORD src1_sel:WORD_1
	s_nop 0
	v_addc_co_u32_e32 v41, vcc, -1, v43, vcc
	global_store_dwordx2 v[40:41], v[38:39], off
	s_waitcnt lgkmcnt(8)
	v_mfma_f32_16x16x32_bf16 v[38:41], v[220:223], v[0:3], 0
	ds_read_b128 v[220:223], v197 offset:16384
	s_waitcnt lgkmcnt(8)
	v_mfma_f32_16x16x32_bf16 v[38:41], v[224:227], v[4:7], v[38:41]
	ds_read_b128 v[224:227], v197 offset:17408
	s_waitcnt lgkmcnt(8)
	v_mfma_f32_16x16x32_bf16 v[38:41], v[228:231], v[8:11], v[38:41]
	ds_read_b128 v[228:231], v197 offset:18432
	s_waitcnt lgkmcnt(8)
	v_mfma_f32_16x16x32_bf16 v[38:41], v[232:235], v[12:15], v[38:41]
	ds_read_b128 v[232:235], v197 offset:19456
	s_waitcnt lgkmcnt(8)
	v_mfma_f32_16x16x32_bf16 v[38:41], v[236:239], v[16:19], v[38:41]
	ds_read_b128 v[236:239], v197 offset:20480
	s_waitcnt lgkmcnt(8)
	v_mfma_f32_16x16x32_bf16 v[38:41], v[240:243], v[20:23], v[38:41]
	ds_read_b128 v[240:243], v197 offset:21504
	s_waitcnt lgkmcnt(8)
	v_mfma_f32_16x16x32_bf16 v[38:41], v[244:247], v[24:27], v[38:41]
	ds_read_b128 v[244:247], v197 offset:22528
	ds_read_b64 v[42:43], v149
	s_waitcnt lgkmcnt(0)
	v_lshl_add_u64 v[42:43], v[42:43], 0, v[36:37]
	s_waitcnt lgkmcnt(8)
; #define MFMA(a, b, c) __builtin_amdgcn_mfma_f32_16x16x32_bf16((a), (b), (c), 0, 0, 0)
; DI unsigned pack2(float a, float b) { return (unsigned)f2bf(a) | ((unsigned)f2bf(b) << 16); }
; DI void mem_attn_prompt_block(const Params& p, int item, char* smem) {
;     ...
;   const u16* vtp = G(p.VTf) + (size_t)bh * 65536;
; #pragma unroll 1
;   for (int c = 0; c < 4; ++c) {
;     __syncthreads();
; #pragma unroll
;     for (int i = 0; i < 8; ++i) {
;       const int idx = tid + 256 * i;
;       *(bf16x8*)&sK[idx * 8] = *(gb8p)((gu16p)vtp + (size_t)c * 16384 + idx * 8);
;     }
;     __syncthreads();
; #pragma unroll
;     for (int n4 = 0; n4 < 4; ++n4) {
;       f32x4 o = (f32x4){0.f, 0.f, 0.f, 0.f};
; #pragma unroll
;       for (int k2 = 0; k2 < 8; ++k2) o = MFMA(*(const bf16x8*)&sK[((n4 * 8 + k2) * 64 + lane) * 8], pf[k2], o);
;       uint2 ov; ov.x = pack2(o[0] * inv, o[1] * inv); ov.y = pack2(o[2] * inv, o[3] * inv);
;       *(uint2*)&G(p.attn)[(size_t)(row0 + r) * 1024 + h * 256 + (c * 4 + n4) * 16 + kg * 4] = ov;
;       __builtin_amdgcn_sched_barrier(0);
;     }
;   }
	v_mfma_f32_16x16x32_bf16 v[38:41], v[248:251], v[28:31], v[38:41]
	ds_read_b128 v[248:251], v197 offset:23552
	s_nop 7
	v_mov_b32_e32 v45, v40
	v_mov_b32_e32 v40, v39
	v_mov_b32_e32 v44, v38
	v_pk_mul_f32 v[40:41], v[32:33], v[40:41]
	v_pk_mul_f32 v[38:39], v[32:33], v[44:45]
	v_and_b32_sdwa v47, v40, v155 dst_sel:DWORD dst_unused:UNUSED_PAD src0_sel:WORD_1 src1_sel:DWORD
	v_and_b32_sdwa v45, v38, v155 dst_sel:DWORD dst_unused:UNUSED_PAD src0_sel:WORD_1 src1_sel:DWORD
	v_and_b32_sdwa v46, v41, v155 dst_sel:DWORD dst_unused:UNUSED_PAD src0_sel:WORD_1 src1_sel:DWORD
	v_add3_u32 v40, v40, v47, s38
	v_and_b32_sdwa v44, v39, v155 dst_sel:DWORD dst_unused:UNUSED_PAD src0_sel:WORD_1 src1_sel:DWORD
	v_add3_u32 v38, v38, v45, s38
	v_add3_u32 v41, v41, v46, s38
	v_and_b32_e32 v40, 0xffff0000, v40
	v_add3_u32 v39, v39, v44, s38
	v_and_b32_e32 v41, 0xffff0000, v41
	v_or_b32_sdwa v38, v40, v38 dst_sel:DWORD dst_unused:UNUSED_PAD src0_sel:DWORD src1_sel:WORD_1
	v_add_co_u32_e32 v40, vcc, s45, v42
	v_or_b32_sdwa v39, v41, v39 dst_sel:DWORD dst_unused:UNUSED_PAD src0_sel:DWORD src1_sel:WORD_1
	s_nop 0
	v_addc_co_u32_e32 v41, vcc, -1, v43, vcc
	global_store_dwordx2 v[40:41], v[38:39], off
	s_waitcnt lgkmcnt(8)
	v_mfma_f32_16x16x32_bf16 v[38:41], v[220:223], v[0:3], 0
	ds_read_b128 v[220:223], v197 offset:24576
	s_waitcnt lgkmcnt(8)
	v_mfma_f32_16x16x32_bf16 v[38:41], v[224:227], v[4:7], v[38:41]
	ds_read_b128 v[224:227], v197 offset:25600
	s_waitcnt lgkmcnt(8)
	v_mfma_f32_16x16x32_bf16 v[38:41], v[228:231], v[8:11], v[38:41]
	ds_read_b128 v[228:231], v197 offset:26624
	s_waitcnt lgkmcnt(8)
	v_mfma_f32_16x16x32_bf16 v[38:41], v[232:235], v[12:15], v[38:41]
	ds_read_b128 v[232:235], v197 offset:27648
	s_waitcnt lgkmcnt(8)
	v_mfma_f32_16x16x32_bf16 v[38:41], v[236:239], v[16:19], v[38:41]
	ds_read_b128 v[236:239], v197 offset:28672
	s_waitcnt lgkmcnt(8)
	v_mfma_f32_16x16x32_bf16 v[38:41], v[240:243], v[20:23], v[38:41]
	ds_read_b128 v[240:243], v197 offset:29696
	s_waitcnt lgkmcnt(8)
	v_mfma_f32_16x16x32_bf16 v[38:41], v[244:247], v[24:27], v[38:41]
	ds_read_b128 v[244:247], v197 offset:30720
	ds_read_b64 v[42:43], v149
	s_waitcnt lgkmcnt(0)
	v_lshl_add_u64 v[42:43], v[42:43], 0, v[36:37]
	s_waitcnt lgkmcnt(8)
	v_mfma_f32_16x16x32_bf16 v[38:41], v[248:251], v[28:31], v[38:41]
	ds_read_b128 v[248:251], v197 offset:31744
	s_nop 7
	v_mov_b32_e32 v45, v40
	v_mov_b32_e32 v40, v39
	v_mov_b32_e32 v44, v38
	v_pk_mul_f32 v[40:41], v[32:33], v[40:41]
	v_pk_mul_f32 v[38:39], v[32:33], v[44:45]
	v_and_b32_sdwa v47, v40, v155 dst_sel:DWORD dst_unused:UNUSED_PAD src0_sel:WORD_1 src1_sel:DWORD
	v_and_b32_sdwa v45, v38, v155 dst_sel:DWORD dst_unused:UNUSED_PAD src0_sel:WORD_1 src1_sel:DWORD
	v_and_b32_sdwa v46, v41, v155 dst_sel:DWORD dst_unused:UNUSED_PAD src0_sel:WORD_1 src1_sel:DWORD
	v_add3_u32 v40, v40, v47, s38
	v_and_b32_sdwa v44, v39, v155 dst_sel:DWORD dst_unused:UNUSED_PAD src0_sel:WORD_1 src1_sel:DWORD
	v_add3_u32 v38, v38, v45, s38
	v_add3_u32 v41, v41, v46, s38
	v_and_b32_e32 v40, 0xffff0000, v40
	v_add3_u32 v39, v39, v44, s38
	v_and_b32_e32 v41, 0xffff0000, v41
	v_or_b32_sdwa v38, v40, v38 dst_sel:DWORD dst_unused:UNUSED_PAD src0_sel:DWORD src1_sel:WORD_1
	v_add_co_u32_e32 v40, vcc, s46, v42
	v_or_b32_sdwa v39, v41, v39 dst_sel:DWORD dst_unused:UNUSED_PAD src0_sel:DWORD src1_sel:WORD_1
	s_nop 0
	v_addc_co_u32_e32 v41, vcc, -1, v43, vcc
	global_store_dwordx2 v[40:41], v[38:39], off
	s_waitcnt lgkmcnt(8)
	v_mfma_f32_16x16x32_bf16 v[38:41], v[220:223], v[0:3], 0
	s_waitcnt lgkmcnt(7)
	v_mfma_f32_16x16x32_bf16 v[38:41], v[224:227], v[4:7], v[38:41]
	s_waitcnt lgkmcnt(6)
	v_mfma_f32_16x16x32_bf16 v[38:41], v[228:231], v[8:11], v[38:41]
	s_waitcnt lgkmcnt(5)
	v_mfma_f32_16x16x32_bf16 v[38:41], v[232:235], v[12:15], v[38:41]
	s_waitcnt lgkmcnt(4)
	v_mfma_f32_16x16x32_bf16 v[38:41], v[236:239], v[16:19], v[38:41]
	s_waitcnt lgkmcnt(3)
	v_mfma_f32_16x16x32_bf16 v[38:41], v[240:243], v[20:23], v[38:41]
	s_waitcnt lgkmcnt(2)
	v_mfma_f32_16x16x32_bf16 v[38:41], v[244:247], v[24:27], v[38:41]
	ds_read_b64 v[42:43], v149
	s_waitcnt lgkmcnt(0)
	v_lshl_add_u64 v[42:43], v[42:43], 0, v[36:37]
	s_waitcnt lgkmcnt(1)
	v_mfma_f32_16x16x32_bf16 v[38:41], v[248:251], v[28:31], v[38:41]
	s_nop 7
	v_mov_b32_e32 v45, v40
	v_mov_b32_e32 v40, v39
	v_mov_b32_e32 v44, v38
	v_pk_mul_f32 v[40:41], v[32:33], v[40:41]
	v_pk_mul_f32 v[38:39], v[32:33], v[44:45]
	v_and_b32_sdwa v46, v41, v155 dst_sel:DWORD dst_unused:UNUSED_PAD src0_sel:WORD_1 src1_sel:DWORD
	v_and_b32_sdwa v47, v40, v155 dst_sel:DWORD dst_unused:UNUSED_PAD src0_sel:WORD_1 src1_sel:DWORD
	v_and_b32_sdwa v44, v39, v155 dst_sel:DWORD dst_unused:UNUSED_PAD src0_sel:WORD_1 src1_sel:DWORD
	v_and_b32_sdwa v45, v38, v155 dst_sel:DWORD dst_unused:UNUSED_PAD src0_sel:WORD_1 src1_sel:DWORD
	v_add3_u32 v41, v41, v46, s38
	v_add3_u32 v40, v40, v47, s38
	v_add3_u32 v38, v38, v45, s38
	v_add3_u32 v39, v39, v44, s38
	v_and_b32_e32 v41, 0xffff0000, v41
	v_and_b32_e32 v40, 0xffff0000, v40
	v_or_b32_sdwa v39, v41, v39 dst_sel:DWORD dst_unused:UNUSED_PAD src0_sel:DWORD src1_sel:WORD_1
	v_or_b32_sdwa v38, v40, v38 dst_sel:DWORD dst_unused:UNUSED_PAD src0_sel:DWORD src1_sel:WORD_1
	global_store_dwordx2 v[42:43], v[38:39], off
	s_add_u32 s24, s24, 0x8000
	s_addc_u32 s25, s25, 0
	s_cmp_lg_u32 s24, 0x20000
	v_lshl_add_u64 v[36:37], v[36:37], 0, s[2:3]
	s_cbranch_scc1 .LBB0_889
	s_mov_b64 s[24:25], 0
